# sample w_in task: all 24 operand loads first, per step sum of squares + v_cvt_pk_bf16_f32 pack + MFMA (was three waits per step)
# baseline (speedup 1.0000x reference)
; DEV unsigned pk2(float lo, float hi) { return (unsigned)f2bf(lo) | ((unsigned)f2bf(hi) << 16); }
; DEV float shfl_xor_(float v, int m) { return __builtin_bit_cast(float, __builtin_amdgcn_ds_bpermute((lane_id() ^ m) << 2, __builtin_bit_cast(int, v))); }
; #define LAS __attribute__((address_space(3)))
; template <bool F32A, bool PAIR, class Epi> DEV void sgemm_wg(const void* Aptr, int lda, const bf16_t* Bt, int ldb, int K, int n0, int n1, int wave, int lane, LAS float* red, Epi epi) {
;     ...
;     for (int k = kb; k < kb + kper; k += 16) {
;         bf16x8 a;
;         if (F32A) { const float* ap = (const float*)Aptr + (size_t)r32 * lda + k + 8 * hi; const f32x4 x0 = *(const f32x4*)ap, x1 = *(const f32x4*)(ap + 4);
;             ss += (x0.x * x0.x + x0.y * x0.y) + (x0.z * x0.z + x0.w * x0.w) + (x1.x * x1.x + x1.y * x1.y) + (x1.z * x1.z + x1.w * x1.w);
;             u32x4 w; w.x = pk2(x0.x, x0.y); w.y = pk2(x0.z, x0.w); w.z = pk2(x1.x, x1.y); w.w = pk2(x1.z, x1.w); a = __builtin_bit_cast(bf16x8, w); }
;         else a = *(const bf16x8*)((const bf16_t*)Aptr + (size_t)r32 * lda + k + 8 * hi);
;         acc0 = __builtin_amdgcn_mfma_f32_32x32x16_bf16(a, *(const bf16x8*)(bp0 + k), acc0, 0, 0, 0);
;         if (PAIR) acc1 = __builtin_amdgcn_mfma_f32_32x32x16_bf16(a, *(const bf16x8*)(bp1 + k), acc1, 0, 0, 0);
;     }
;     LAS float* ssw = red + 2 * 8 * 1024;
; #pragma unroll
;     for (int r = 0; r < 16; ++r) { red[(wave * 16 + r) * 64 + lane] = acc0[r]; if (PAIR) red[8 * 1024 + (wave * 16 + r) * 64 + lane] = acc1[r]; }
;     if (F32A) { ss += shfl_xor_(ss, 32); if (lane < 32) ssw[wave * 32 + lane] = ss; }
; __global__ void __launch_bounds__(512, 2) mk_fwd(MKArgs args) {
;     ...
;             { PHASE_IDS float* PS = (float*)(ws + WS_PS);
;               const int k0_ = rd ? bx - 128 : G - 1 - bx;
;               if (rd && l > 0 && k0_ >= 0 && k0_ < DINP / 32) wg_wait(ctl + CW_S6 + 64 * (l - 1), DM / 32, nullptr, 0u, wave_s);
;               for (int k = k0_; k >= 0 && k < DINP / 32; k += G)
;                 sgemm_wg<true, false>(xin_s, DM, (const bf16_t*)(wl + WL_IN), DM, DM, 32 * k, 0, wave, lane, (LAS float*)(ldsl + RING_OFF), [&](int row, int c, float v, float, float ssq) { PS[(size_t)row * DINP + 32 * k + c] = v * rsqrtf(ssq * (1.f / DM) + EPS); }); }
.LBB0_701:
	s_waitcnt vmcnt(0)
	s_barrier
	v_lshl_add_u64 v[24:25], v[0:1], 1, v[36:37]
	global_load_dwordx4 v[60:63], v[28:29], off
	global_load_dwordx4 v[64:67], v[28:29], off offset:16
	global_load_dwordx4 v[68:71], v[28:29], off offset:64
	global_load_dwordx4 v[72:75], v[28:29], off offset:80
	global_load_dwordx4 v[76:79], v[28:29], off offset:128
	global_load_dwordx4 v[80:83], v[28:29], off offset:144
	global_load_dwordx4 v[84:87], v[28:29], off offset:192
	global_load_dwordx4 v[88:91], v[28:29], off offset:208
	global_load_dwordx4 v[92:95], v[28:29], off offset:256
	global_load_dwordx4 v[96:99], v[28:29], off offset:272
	global_load_dwordx4 v[100:103], v[28:29], off offset:320
	global_load_dwordx4 v[104:107], v[28:29], off offset:336
	global_load_dwordx4 v[108:111], v[28:29], off offset:384
	global_load_dwordx4 v[112:115], v[28:29], off offset:400
	global_load_dwordx4 v[116:119], v[28:29], off offset:448
	global_load_dwordx4 v[120:123], v[28:29], off offset:464
	global_load_dwordx4 v[124:127], v[24:25], off
	global_load_dwordx4 v[128:131], v[24:25], off offset:32
	global_load_dwordx4 v[132:135], v[24:25], off offset:64
	global_load_dwordx4 v[136:139], v[24:25], off offset:96
	global_load_dwordx4 v[140:143], v[24:25], off offset:128
	global_load_dwordx4 v[144:147], v[24:25], off offset:160
	global_load_dwordx4 v[148:151], v[24:25], off offset:192
	global_load_dwordx4 v[152:155], v[24:25], off offset:224
	v_mov_b32_e32 v156, 0
	s_waitcnt vmcnt(7)
	v_mul_f32_e32 v157, v61, v61
	v_mul_f32_e32 v158, v63, v63
	v_fmac_f32_e32 v157, v60, v60
	v_fmac_f32_e32 v158, v62, v62
	v_add_f32_e32 v157, v157, v158
	v_mul_f32_e32 v158, v65, v65
	v_fmac_f32_e32 v158, v64, v64
	v_add_f32_e32 v157, v157, v158
	v_mul_f32_e32 v158, v67, v67
	v_fmac_f32_e32 v158, v66, v66
	v_add_f32_e32 v157, v158, v157
	v_add_f32_e32 v156, v156, v157
	v_cvt_pk_bf16_f32 v60, v60, v61
	v_cvt_pk_bf16_f32 v61, v62, v63
	v_cvt_pk_bf16_f32 v62, v64, v65
	v_cvt_pk_bf16_f32 v63, v66, v67
	s_nop 1
	v_mfma_f32_32x32x16_bf16 v[2:17], v[60:63], v[124:127], 0
	s_waitcnt vmcnt(6)
	v_mul_f32_e32 v157, v69, v69
	v_mul_f32_e32 v158, v71, v71
	v_fmac_f32_e32 v157, v68, v68
	v_fmac_f32_e32 v158, v70, v70
	v_add_f32_e32 v157, v157, v158
	v_mul_f32_e32 v158, v73, v73
	v_fmac_f32_e32 v158, v72, v72
	v_add_f32_e32 v157, v157, v158
	v_mul_f32_e32 v158, v75, v75
	v_fmac_f32_e32 v158, v74, v74
	v_add_f32_e32 v157, v158, v157
	v_add_f32_e32 v156, v156, v157
	v_cvt_pk_bf16_f32 v68, v68, v69
	v_cvt_pk_bf16_f32 v69, v70, v71
	v_cvt_pk_bf16_f32 v70, v72, v73
	v_cvt_pk_bf16_f32 v71, v74, v75
	s_nop 1
	v_mfma_f32_32x32x16_bf16 v[2:17], v[68:71], v[128:131], v[2:17]
	s_waitcnt vmcnt(5)
	v_mul_f32_e32 v157, v77, v77
	v_mul_f32_e32 v158, v79, v79
	v_fmac_f32_e32 v157, v76, v76
	v_fmac_f32_e32 v158, v78, v78
	v_add_f32_e32 v157, v157, v158
	v_mul_f32_e32 v158, v81, v81
	v_fmac_f32_e32 v158, v80, v80
	v_add_f32_e32 v157, v157, v158
	v_mul_f32_e32 v158, v83, v83
	v_fmac_f32_e32 v158, v82, v82
	v_add_f32_e32 v157, v158, v157
	v_add_f32_e32 v156, v156, v157
	v_cvt_pk_bf16_f32 v76, v76, v77
	v_cvt_pk_bf16_f32 v77, v78, v79
	v_cvt_pk_bf16_f32 v78, v80, v81
	v_cvt_pk_bf16_f32 v79, v82, v83
	s_nop 1
	v_mfma_f32_32x32x16_bf16 v[2:17], v[76:79], v[132:135], v[2:17]
	s_waitcnt vmcnt(4)
	v_mul_f32_e32 v157, v85, v85
	v_mul_f32_e32 v158, v87, v87
	v_fmac_f32_e32 v157, v84, v84
	v_fmac_f32_e32 v158, v86, v86
	v_add_f32_e32 v157, v157, v158
	v_mul_f32_e32 v158, v89, v89
	v_fmac_f32_e32 v158, v88, v88
	v_add_f32_e32 v157, v157, v158
	v_mul_f32_e32 v158, v91, v91
	v_fmac_f32_e32 v158, v90, v90
	v_add_f32_e32 v157, v158, v157
	v_add_f32_e32 v156, v156, v157
	v_cvt_pk_bf16_f32 v84, v84, v85
	v_cvt_pk_bf16_f32 v85, v86, v87
	v_cvt_pk_bf16_f32 v86, v88, v89
	v_cvt_pk_bf16_f32 v87, v90, v91
	s_nop 1
	v_mfma_f32_32x32x16_bf16 v[2:17], v[84:87], v[136:139], v[2:17]
	s_waitcnt vmcnt(3)
	v_mul_f32_e32 v157, v93, v93
	v_mul_f32_e32 v158, v95, v95
	v_fmac_f32_e32 v157, v92, v92
	v_fmac_f32_e32 v158, v94, v94
	v_add_f32_e32 v157, v157, v158
	v_mul_f32_e32 v158, v97, v97
	v_fmac_f32_e32 v158, v96, v96
	v_add_f32_e32 v157, v157, v158
	v_mul_f32_e32 v158, v99, v99
	v_fmac_f32_e32 v158, v98, v98
	v_add_f32_e32 v157, v158, v157
	v_add_f32_e32 v156, v156, v157
	v_cvt_pk_bf16_f32 v92, v92, v93
	v_cvt_pk_bf16_f32 v93, v94, v95
	v_cvt_pk_bf16_f32 v94, v96, v97
	v_cvt_pk_bf16_f32 v95, v98, v99
	s_nop 1
	v_mfma_f32_32x32x16_bf16 v[2:17], v[92:95], v[140:143], v[2:17]
	s_waitcnt vmcnt(2)
	v_mul_f32_e32 v157, v101, v101
	v_mul_f32_e32 v158, v103, v103
	v_fmac_f32_e32 v157, v100, v100
	v_fmac_f32_e32 v158, v102, v102
	v_add_f32_e32 v157, v157, v158
	v_mul_f32_e32 v158, v105, v105
	v_fmac_f32_e32 v158, v104, v104
	v_add_f32_e32 v157, v157, v158
	v_mul_f32_e32 v158, v107, v107
	v_fmac_f32_e32 v158, v106, v106
	v_add_f32_e32 v157, v158, v157
	v_add_f32_e32 v156, v156, v157
	v_cvt_pk_bf16_f32 v100, v100, v101
	v_cvt_pk_bf16_f32 v101, v102, v103
	v_cvt_pk_bf16_f32 v102, v104, v105
	v_cvt_pk_bf16_f32 v103, v106, v107
	s_nop 1
	v_mfma_f32_32x32x16_bf16 v[2:17], v[100:103], v[144:147], v[2:17]
	s_waitcnt vmcnt(1)
	v_mul_f32_e32 v157, v109, v109
	v_mul_f32_e32 v158, v111, v111
	v_fmac_f32_e32 v157, v108, v108
	v_fmac_f32_e32 v158, v110, v110
	v_add_f32_e32 v157, v157, v158
	v_mul_f32_e32 v158, v113, v113
	v_fmac_f32_e32 v158, v112, v112
	v_add_f32_e32 v157, v157, v158
	v_mul_f32_e32 v158, v115, v115
	v_fmac_f32_e32 v158, v114, v114
	v_add_f32_e32 v157, v158, v157
	v_add_f32_e32 v156, v156, v157
	v_cvt_pk_bf16_f32 v108, v108, v109
	v_cvt_pk_bf16_f32 v109, v110, v111
	v_cvt_pk_bf16_f32 v110, v112, v113
	v_cvt_pk_bf16_f32 v111, v114, v115
	s_nop 1
	v_mfma_f32_32x32x16_bf16 v[2:17], v[108:111], v[148:151], v[2:17]
	s_waitcnt vmcnt(0)
	v_mul_f32_e32 v157, v117, v117
	v_mul_f32_e32 v158, v119, v119
	v_fmac_f32_e32 v157, v116, v116
	v_fmac_f32_e32 v158, v118, v118
	v_add_f32_e32 v157, v157, v158
	v_mul_f32_e32 v158, v121, v121
	v_fmac_f32_e32 v158, v120, v120
	v_add_f32_e32 v157, v157, v158
	v_mul_f32_e32 v158, v123, v123
	v_fmac_f32_e32 v158, v122, v122
	v_add_f32_e32 v157, v158, v157
	v_add_f32_e32 v156, v156, v157
	v_cvt_pk_bf16_f32 v116, v116, v117
	v_cvt_pk_bf16_f32 v117, v118, v119
	v_cvt_pk_bf16_f32 v118, v120, v121
	v_cvt_pk_bf16_f32 v119, v122, v123
	s_nop 1
	v_mfma_f32_32x32x16_bf16 v[2:17], v[116:119], v[152:155], v[2:17]
	v_add_u32_e32 v20, s2, v38
	s_nop 10
	ds_write2st64_b32 v20, v2, v3 offset1:1
	ds_write2st64_b32 v20, v4, v5 offset0:2 offset1:3
	ds_write2st64_b32 v20, v6, v7 offset0:4 offset1:5
	ds_write2st64_b32 v20, v8, v9 offset0:6 offset1:7
	ds_write2st64_b32 v20, v10, v11 offset0:8 offset1:9
	ds_write2st64_b32 v20, v12, v13 offset0:10 offset1:11
	ds_write2st64_b32 v20, v14, v15 offset0:12 offset1:13
	ds_write2st64_b32 v20, v16, v17 offset0:14 offset1:15
	v_mov_b32_e32 v2, v156
	v_mbcnt_lo_u32_b32 v3, -1, 0
	v_mbcnt_hi_u32_b32 v3, -1, v3
	v_lshlrev_b32_e32 v3, 2, v3
	v_xor_b32_e32 v3, 0x80, v3
	ds_bpermute_b32 v3, v3, v2
	s_and_saveexec_b64 s[0:1], vcc
	s_cbranch_execz .LBB0_700
; DEV float shfl_xor_(float v, int m) { return __builtin_bit_cast(float, __builtin_amdgcn_ds_bpermute((lane_id() ^ m) << 2, __builtin_bit_cast(int, v))); }
; template <bool F32A, bool PAIR, class Epi> DEV void sgemm_wg(const void* Aptr, int lda, const bf16_t* Bt, int ldb, int K, int n0, int n1, int wave, int lane, LAS float* red, Epi epi) {
;     ...
;     if (F32A) { ss += shfl_xor_(ss, 32); if (lane < 32) ssw[wave * 32 + lane] = ss; }
	s_waitcnt lgkmcnt(0)
	v_add_f32_e32 v2, v2, v3
	ds_write_b32 v39, v2
	s_branch .LBB0_700
